# P7/P8/P1 GEMM K-loops: LDS-DMA staging re-balanced to 4 pieces per super-phase (As[*][0] staged one super-phase later, SP2 waits vmcnt(6))
# baseline (speedup 1.0000x reference)
; #define PG8_STAGE(bufoff, gbase, voff) do { _Pragma("unroll") for (int _i = 0; _i < 2; ++_i) \
;         __builtin_amdgcn_global_load_lds((const unsigned*)((const char*)(gbase) + (voff)[_i]), (PG8_LAS unsigned*)(lds + (bufoff) + ldsw + _i * 8192), 16, 0, 0); } while (0)
; #define PG8_LDA(dst, b, h) do { _Pragma("unroll") for (int m = 0; m < 4; ++m) _Pragma("unroll") for (int k = 0; k < 2; ++k) dst[m][k] = *(const PG8_LAS bf16x8*)(lds + PG8_SA(b, h) + aoff + m * 2048 + k * 1024); } while (0)
; #define PG8_LDB(dst, b, h) do { _Pragma("unroll") for (int n = 0; n < 2; ++n) _Pragma("unroll") for (int k = 0; k < 2; ++k) dst[n][k] = *(const PG8_LAS bf16x8*)(lds + PG8_SB(b, h) + boff + n * 2048 + k * 1024); } while (0)
; #define PG8_MMA(ai, bj, At, Bt) do { __builtin_amdgcn_s_setprio(1); _Pragma("unroll") for (int m = 0; m < 4; ++m) _Pragma("unroll") for (int n = 0; n < 2; ++n) _Pragma("unroll") for (int k = 0; k < 2; ++k) \
;         acc[ai][bj][m][n] = __builtin_amdgcn_mfma_f32_16x16x32_bf16(Bt[n][k], At[m][k], acc[ai][bj][m][n], 0, 0, 0); __builtin_amdgcn_s_setprio(0); } while (0)
; template <class Epi, class Sched, bool ALIGN_EPI = false, bool SP2 = false>
; __device__ __forceinline__ void gemm_phase(PG8_LAS unsigned char* lds, const Gemm g, const Sched& S, const Epi& E) {
;     ...
;             if constexpr (SP2) {
;             PG8_LDB(B0, 0, 0); PG8_LDB(B1, 0, 1); PG8_SCHED; PG8_LDA(At, 0, 0); PG8_STAGE(PG8_SA(1, 1), a1 + hstepA, voffA);
;             PG8_WAIT_V(8); PG8_WAIT_L(0); PG8_BAR; PG8_MMA(0, 0, At, B0); PG8_MMA(0, 1, At, B1); PG8_BAR; PG8_SCHED;
;             PG8_LDA(At, 0, 1); PG8_STAGE(PG8_SB(0, 0), b2, voffB); PG8_STAGE(PG8_SB(0, 1), b2 + hstepB, voffB); PG8_STAGE(PG8_SA(0, 0), a2, voffA);
;             PG8_WAIT_V(8); PG8_WAIT_L(0); PG8_BAR; PG8_MMA(1, 0, At, B0); PG8_MMA(1, 1, At, B1); PG8_BAR; PG8_SCHED;
;             PG8_LDB(B0, 1, 0); PG8_LDB(B1, 1, 1); PG8_SCHED; PG8_LDA(At, 1, 0); PG8_STAGE(PG8_SA(0, 1), a2 + hstepA, voffA);
;             PG8_WAIT_V(8); PG8_WAIT_L(0); PG8_BAR; PG8_MMA(0, 0, At, B0); PG8_MMA(0, 1, At, B1); PG8_BAR; PG8_SCHED;
;             PG8_LDA(At, 1, 1); PG8_STAGE(PG8_SB(1, 0), b3, voffB); PG8_STAGE(PG8_SB(1, 1), b3 + hstepB, voffB); PG8_STAGE(PG8_SA(1, 0), a3, voffA);
;             PG8_WAIT_V(8); PG8_WAIT_L(0); PG8_BAR; PG8_MMA(1, 0, At, B0); PG8_MMA(1, 1, At, B1); PG8_BAR; PG8_SCHED;
.LBB0_187:
	ds_read_b128 v[128:131], v173
	ds_read_b128 v[132:135], v173 offset:1024
	ds_read_b128 v[152:155], v173 offset:2048
	ds_read_b128 v[156:159], v173 offset:3072
	ds_read_b128 v[160:163], v174
	ds_read_b128 v[164:167], v174 offset:1024
	ds_read_b128 v[180:183], v174 offset:2048
	ds_read_b128 v[184:187], v174 offset:3072
	s_add_u32 s16, s12, 0xfff80080
	s_addc_u32 s17, s13, -1
	s_cmp_eq_u32 s61, 28
	s_cselect_b32 s19, s1, s17
	s_cselect_b32 s18, s26, s16
	s_cselect_b32 s17, s15, s60
	s_cselect_b32 s16, s36, s37
	v_lshl_add_u64 v[168:169], s[12:13], 0, v[144:145]
	s_add_i32 m0, s77, 0xc000
	ds_read_b128 v[188:191], v175
	ds_read_b128 v[192:195], v175 offset:1024
	ds_read_b128 v[196:199], v175 offset:2048
	ds_read_b128 v[200:203], v175 offset:3072
	ds_read_b128 v[204:207], v175 offset:4096
	ds_read_b128 v[208:211], v175 offset:5120
	ds_read_b128 v[212:215], v175 offset:6144
	ds_read_b128 v[216:219], v175 offset:7168
	s_add_u32 s98, s12, 0xfff80000
	s_addc_u32 s99, s13, -1
	s_mov_b32 m0, s7
	s_nop 0
	global_load_lds_dwordx4 v136, s[98:99]
	s_mov_b32 m0, s46
	s_nop 0
	global_load_lds_dwordx4 v140, s[98:99]
	s_add_i32 m0, s77, 0xc000
	s_nop 0
	global_load_lds_dwordx4 v[168:169], off
	v_lshl_add_u64 v[168:169], s[12:13], 0, v[146:147]
	s_add_i32 m0, s77, 0xe000
	s_nop 0
	global_load_lds_dwordx4 v[168:169], off
	s_waitcnt vmcnt(8)
	s_waitcnt lgkmcnt(0)
	s_barrier
	s_setprio 1
	s_waitcnt lgkmcnt(0)
	v_mfma_f32_16x16x32_bf16 v[124:127], v[128:131], v[188:191], v[124:127]
	v_mfma_f32_16x16x32_bf16 v[120:123], v[152:155], v[188:191], v[120:123]
	v_mfma_f32_16x16x32_bf16 v[108:111], v[128:131], v[196:199], v[108:111]
	v_mfma_f32_16x16x32_bf16 v[104:107], v[152:155], v[196:199], v[104:107]
	v_mfma_f32_16x16x32_bf16 v[92:95], v[128:131], v[204:207], v[92:95]
	v_mfma_f32_16x16x32_bf16 v[88:91], v[152:155], v[204:207], v[88:91]
	v_mfma_f32_16x16x32_bf16 v[76:79], v[128:131], v[212:215], v[76:79]
	v_mfma_f32_16x16x32_bf16 v[72:75], v[152:155], v[212:215], v[72:75]
	v_mfma_f32_16x16x32_bf16 v[124:127], v[132:135], v[192:195], v[124:127]
	v_mfma_f32_16x16x32_bf16 v[120:123], v[156:159], v[192:195], v[120:123]
	v_mfma_f32_16x16x32_bf16 v[108:111], v[132:135], v[200:203], v[108:111]
	v_mfma_f32_16x16x32_bf16 v[104:107], v[156:159], v[200:203], v[104:107]
	v_mfma_f32_16x16x32_bf16 v[92:95], v[132:135], v[208:211], v[92:95]
	v_mfma_f32_16x16x32_bf16 v[88:91], v[156:159], v[208:211], v[88:91]
	v_mfma_f32_16x16x32_bf16 v[76:79], v[132:135], v[216:219], v[76:79]
	v_mfma_f32_16x16x32_bf16 v[72:75], v[156:159], v[216:219], v[72:75]
	s_setprio 0
	s_setprio 1
	v_mfma_f32_16x16x32_bf16 v[116:119], v[160:163], v[188:191], v[116:119]
	v_mfma_f32_16x16x32_bf16 v[112:115], v[180:183], v[188:191], v[112:115]
	v_mfma_f32_16x16x32_bf16 v[100:103], v[160:163], v[196:199], v[100:103]
	v_mfma_f32_16x16x32_bf16 v[96:99], v[180:183], v[196:199], v[96:99]
	v_mfma_f32_16x16x32_bf16 v[84:87], v[160:163], v[204:207], v[84:87]
	v_mfma_f32_16x16x32_bf16 v[80:83], v[180:183], v[204:207], v[80:83]
	v_mfma_f32_16x16x32_bf16 v[68:71], v[160:163], v[212:215], v[68:71]
	v_mfma_f32_16x16x32_bf16 v[64:67], v[180:183], v[212:215], v[64:67]
	v_mfma_f32_16x16x32_bf16 v[116:119], v[164:167], v[192:195], v[116:119]
	v_mfma_f32_16x16x32_bf16 v[112:115], v[184:187], v[192:195], v[112:115]
	v_mfma_f32_16x16x32_bf16 v[100:103], v[164:167], v[200:203], v[100:103]
	v_mfma_f32_16x16x32_bf16 v[96:99], v[184:187], v[200:203], v[96:99]
	v_mfma_f32_16x16x32_bf16 v[84:87], v[164:167], v[208:211], v[84:87]
	v_mfma_f32_16x16x32_bf16 v[80:83], v[184:187], v[208:211], v[80:83]
	v_mfma_f32_16x16x32_bf16 v[68:71], v[164:167], v[216:219], v[68:71]
	v_mfma_f32_16x16x32_bf16 v[64:67], v[184:187], v[216:219], v[64:67]
	s_setprio 0
	s_barrier
	s_add_i32 s69, s47, s33
	v_lshl_add_u64 v[168:169], s[16:17], 0, v[138:139]
	s_mov_b32 m0, s69
	ds_read_b128 v[188:191], v175 offset:16384
	ds_read_b128 v[192:195], v175 offset:17408
	ds_read_b128 v[196:199], v175 offset:18432
	ds_read_b128 v[200:203], v175 offset:19456
	ds_read_b128 v[204:207], v175 offset:20480
	ds_read_b128 v[208:211], v175 offset:21504
	ds_read_b128 v[212:215], v175 offset:22528
	ds_read_b128 v[216:219], v175 offset:23552
	global_load_lds_dwordx4 v[168:169], off
	s_add_i32 m0, s69, 0x2000
	s_add_u32 s70, s16, 0x80000
	v_lshl_add_u64 v[220:221], s[16:17], 0, v[142:143]
	s_addc_u32 s71, s17, 0
	s_add_i32 s69, s56, s33
	global_load_lds_dwordx4 v[220:221], off
	v_lshl_add_u64 v[222:223], s[70:71], 0, v[138:139]
	s_mov_b32 m0, s69
	global_load_lds_dwordx4 v[222:223], off
	v_lshl_add_u64 v[222:223], s[70:71], 0, v[142:143]
	s_add_i32 m0, s69, 0x2000
	s_nop 0
	global_load_lds_dwordx4 v[222:223], off
	s_waitcnt vmcnt(6)
	s_waitcnt lgkmcnt(0)
	s_barrier
; #define PG8_STAGE(bufoff, gbase, voff) do { _Pragma("unroll") for (int _i = 0; _i < 2; ++_i) \
;         __builtin_amdgcn_global_load_lds((const unsigned*)((const char*)(gbase) + (voff)[_i]), (PG8_LAS unsigned*)(lds + (bufoff) + ldsw + _i * 8192), 16, 0, 0); } while (0)
; #define PG8_LDA(dst, b, h) do { _Pragma("unroll") for (int m = 0; m < 4; ++m) _Pragma("unroll") for (int k = 0; k < 2; ++k) dst[m][k] = *(const PG8_LAS bf16x8*)(lds + PG8_SA(b, h) + aoff + m * 2048 + k * 1024); } while (0)
; #define PG8_LDB(dst, b, h) do { _Pragma("unroll") for (int n = 0; n < 2; ++n) _Pragma("unroll") for (int k = 0; k < 2; ++k) dst[n][k] = *(const PG8_LAS bf16x8*)(lds + PG8_SB(b, h) + boff + n * 2048 + k * 1024); } while (0)
; #define PG8_MMA(ai, bj, At, Bt) do { __builtin_amdgcn_s_setprio(1); _Pragma("unroll") for (int m = 0; m < 4; ++m) _Pragma("unroll") for (int n = 0; n < 2; ++n) _Pragma("unroll") for (int k = 0; k < 2; ++k) \
;         acc[ai][bj][m][n] = __builtin_amdgcn_mfma_f32_16x16x32_bf16(Bt[n][k], At[m][k], acc[ai][bj][m][n], 0, 0, 0); __builtin_amdgcn_s_setprio(0); } while (0)
; template <class Epi, class Sched, bool ALIGN_EPI = false, bool SP2 = false>
; __device__ __forceinline__ void gemm_phase(PG8_LAS unsigned char* lds, const Gemm g, const Sched& S, const Epi& E) {
;     ...
;             if constexpr (SP2) {
;             PG8_LDB(B0, 0, 0); PG8_LDB(B1, 0, 1); PG8_SCHED; PG8_LDA(At, 0, 0); PG8_STAGE(PG8_SA(1, 1), a1 + hstepA, voffA);
;             PG8_WAIT_V(8); PG8_WAIT_L(0); PG8_BAR; PG8_MMA(0, 0, At, B0); PG8_MMA(0, 1, At, B1); PG8_BAR; PG8_SCHED;
;             PG8_LDA(At, 0, 1); PG8_STAGE(PG8_SB(0, 0), b2, voffB); PG8_STAGE(PG8_SB(0, 1), b2 + hstepB, voffB); PG8_STAGE(PG8_SA(0, 0), a2, voffA);
;             PG8_WAIT_V(8); PG8_WAIT_L(0); PG8_BAR; PG8_MMA(1, 0, At, B0); PG8_MMA(1, 1, At, B1); PG8_BAR; PG8_SCHED;
;             PG8_LDB(B0, 1, 0); PG8_LDB(B1, 1, 1); PG8_SCHED; PG8_LDA(At, 1, 0); PG8_STAGE(PG8_SA(0, 1), a2 + hstepA, voffA);
;             PG8_WAIT_V(8); PG8_WAIT_L(0); PG8_BAR; PG8_MMA(0, 0, At, B0); PG8_MMA(0, 1, At, B1); PG8_BAR; PG8_SCHED;
;             PG8_LDA(At, 1, 1); PG8_STAGE(PG8_SB(1, 0), b3, voffB); PG8_STAGE(PG8_SB(1, 1), b3 + hstepB, voffB); PG8_STAGE(PG8_SA(1, 0), a3, voffA);
;             PG8_WAIT_V(8); PG8_WAIT_L(0); PG8_BAR; PG8_MMA(1, 0, At, B0); PG8_MMA(1, 1, At, B1); PG8_BAR; PG8_SCHED;
	s_setprio 1
	s_waitcnt lgkmcnt(0)
	v_mfma_f32_16x16x32_bf16 v[60:63], v[128:131], v[188:191], v[60:63]
	v_mfma_f32_16x16x32_bf16 v[56:59], v[152:155], v[188:191], v[56:59]
	v_mfma_f32_16x16x32_bf16 v[44:47], v[128:131], v[196:199], v[44:47]
	v_mfma_f32_16x16x32_bf16 v[40:43], v[152:155], v[196:199], v[40:43]
	v_mfma_f32_16x16x32_bf16 v[28:31], v[128:131], v[204:207], v[28:31]
	v_mfma_f32_16x16x32_bf16 v[24:27], v[152:155], v[204:207], v[24:27]
	v_mfma_f32_16x16x32_bf16 v[12:15], v[128:131], v[212:215], v[12:15]
	v_mfma_f32_16x16x32_bf16 v[8:11], v[152:155], v[212:215], v[8:11]
	v_mfma_f32_16x16x32_bf16 v[60:63], v[132:135], v[192:195], v[60:63]
	v_mfma_f32_16x16x32_bf16 v[56:59], v[156:159], v[192:195], v[56:59]
	v_mfma_f32_16x16x32_bf16 v[44:47], v[132:135], v[200:203], v[44:47]
	v_mfma_f32_16x16x32_bf16 v[40:43], v[156:159], v[200:203], v[40:43]
	v_mfma_f32_16x16x32_bf16 v[28:31], v[132:135], v[208:211], v[28:31]
	v_mfma_f32_16x16x32_bf16 v[24:27], v[156:159], v[208:211], v[24:27]
	v_mfma_f32_16x16x32_bf16 v[12:15], v[132:135], v[216:219], v[12:15]
	v_mfma_f32_16x16x32_bf16 v[8:11], v[156:159], v[216:219], v[8:11]
	s_setprio 0
	s_setprio 1
	v_mfma_f32_16x16x32_bf16 v[52:55], v[160:163], v[188:191], v[52:55]
	v_mfma_f32_16x16x32_bf16 v[48:51], v[180:183], v[188:191], v[48:51]
	v_mfma_f32_16x16x32_bf16 v[36:39], v[160:163], v[196:199], v[36:39]
	v_mfma_f32_16x16x32_bf16 v[32:35], v[180:183], v[196:199], v[32:35]
	v_mfma_f32_16x16x32_bf16 v[20:23], v[160:163], v[204:207], v[20:23]
	v_mfma_f32_16x16x32_bf16 v[16:19], v[180:183], v[204:207], v[16:19]
	v_mfma_f32_16x16x32_bf16 v[4:7], v[160:163], v[212:215], v[4:7]
	v_mfma_f32_16x16x32_bf16 v[0:3], v[180:183], v[212:215], v[0:3]
	v_mfma_f32_16x16x32_bf16 v[52:55], v[164:167], v[192:195], v[52:55]
	v_mfma_f32_16x16x32_bf16 v[48:51], v[184:187], v[192:195], v[48:51]
	v_mfma_f32_16x16x32_bf16 v[36:39], v[164:167], v[200:203], v[36:39]
	v_mfma_f32_16x16x32_bf16 v[32:35], v[184:187], v[200:203], v[32:35]
	v_mfma_f32_16x16x32_bf16 v[20:23], v[164:167], v[208:211], v[20:23]
	v_mfma_f32_16x16x32_bf16 v[16:19], v[184:187], v[208:211], v[16:19]
	v_mfma_f32_16x16x32_bf16 v[4:7], v[164:167], v[216:219], v[4:7]
	v_mfma_f32_16x16x32_bf16 v[0:3], v[184:187], v[216:219], v[0:3]
	s_setprio 0
	s_barrier
	s_add_i32 s69, 0, 0x18000
	s_add_i32 s70, 0, 0x1c000
	v_add_u32_e32 v156, s69, v172
	v_add_u32_e32 v179, s70, v172
	ds_read_b128 v[128:131], v156
	ds_read_b128 v[132:135], v156 offset:1024
	ds_read_b128 v[152:155], v156 offset:2048
	ds_read_b128 v[156:159], v156 offset:3072
	ds_read_b128 v[160:163], v179
	ds_read_b128 v[164:167], v179 offset:1024
	ds_read_b128 v[180:183], v179 offset:2048
	ds_read_b128 v[184:187], v179 offset:3072
	s_mov_b64 s[100:101], s[18:19]
	s_add_u32 s18, s18, 0x80000
	s_addc_u32 s19, s19, 0
	s_mov_b32 m0, s23
	v_lshl_add_u64 v[226:227], s[18:19], 0, v[136:137]
	ds_read_b128 v[188:191], v175 offset:32768
	ds_read_b128 v[192:195], v175 offset:33792
	ds_read_b128 v[196:199], v175 offset:34816
	ds_read_b128 v[200:203], v175 offset:35840
	ds_read_b128 v[204:207], v175 offset:36864
	ds_read_b128 v[208:211], v175 offset:37888
	ds_read_b128 v[212:215], v175 offset:38912
	ds_read_b128 v[216:219], v175 offset:39936
	s_mov_b32 m0, s77
	s_nop 0
	global_load_lds_dwordx4 v136, s[100:101]
	s_mov_b32 m0, s22
	s_nop 0
	global_load_lds_dwordx4 v140, s[100:101]
	s_mov_b32 m0, s23
	s_nop 0
	global_load_lds_dwordx4 v[226:227], off
	v_lshl_add_u64 v[226:227], s[18:19], 0, v[140:141]
	s_mov_b32 m0, s4
	s_nop 0
	global_load_lds_dwordx4 v[226:227], off
	s_waitcnt vmcnt(8)
	s_waitcnt lgkmcnt(0)
	s_barrier
; #define PG8_STAGE(bufoff, gbase, voff) do { _Pragma("unroll") for (int _i = 0; _i < 2; ++_i) \
;         __builtin_amdgcn_global_load_lds((const unsigned*)((const char*)(gbase) + (voff)[_i]), (PG8_LAS unsigned*)(lds + (bufoff) + ldsw + _i * 8192), 16, 0, 0); } while (0)
; #define PG8_LDA(dst, b, h) do { _Pragma("unroll") for (int m = 0; m < 4; ++m) _Pragma("unroll") for (int k = 0; k < 2; ++k) dst[m][k] = *(const PG8_LAS bf16x8*)(lds + PG8_SA(b, h) + aoff + m * 2048 + k * 1024); } while (0)
; #define PG8_LDB(dst, b, h) do { _Pragma("unroll") for (int n = 0; n < 2; ++n) _Pragma("unroll") for (int k = 0; k < 2; ++k) dst[n][k] = *(const PG8_LAS bf16x8*)(lds + PG8_SB(b, h) + boff + n * 2048 + k * 1024); } while (0)
; #define PG8_MMA(ai, bj, At, Bt) do { __builtin_amdgcn_s_setprio(1); _Pragma("unroll") for (int m = 0; m < 4; ++m) _Pragma("unroll") for (int n = 0; n < 2; ++n) _Pragma("unroll") for (int k = 0; k < 2; ++k) \
;         acc[ai][bj][m][n] = __builtin_amdgcn_mfma_f32_16x16x32_bf16(Bt[n][k], At[m][k], acc[ai][bj][m][n], 0, 0, 0); __builtin_amdgcn_s_setprio(0); } while (0)
; template <class Epi, class Sched, bool ALIGN_EPI = false, bool SP2 = false>
; __device__ __forceinline__ void gemm_phase(PG8_LAS unsigned char* lds, const Gemm g, const Sched& S, const Epi& E) {
;     ...
;             if constexpr (SP2) {
;             PG8_LDB(B0, 0, 0); PG8_LDB(B1, 0, 1); PG8_SCHED; PG8_LDA(At, 0, 0); PG8_STAGE(PG8_SA(1, 1), a1 + hstepA, voffA);
;             PG8_WAIT_V(8); PG8_WAIT_L(0); PG8_BAR; PG8_MMA(0, 0, At, B0); PG8_MMA(0, 1, At, B1); PG8_BAR; PG8_SCHED;
;             PG8_LDA(At, 0, 1); PG8_STAGE(PG8_SB(0, 0), b2, voffB); PG8_STAGE(PG8_SB(0, 1), b2 + hstepB, voffB); PG8_STAGE(PG8_SA(0, 0), a2, voffA);
;             PG8_WAIT_V(8); PG8_WAIT_L(0); PG8_BAR; PG8_MMA(1, 0, At, B0); PG8_MMA(1, 1, At, B1); PG8_BAR; PG8_SCHED;
;             PG8_LDB(B0, 1, 0); PG8_LDB(B1, 1, 1); PG8_SCHED; PG8_LDA(At, 1, 0); PG8_STAGE(PG8_SA(0, 1), a2 + hstepA, voffA);
;             PG8_WAIT_V(8); PG8_WAIT_L(0); PG8_BAR; PG8_MMA(0, 0, At, B0); PG8_MMA(0, 1, At, B1); PG8_BAR; PG8_SCHED;
;             PG8_LDA(At, 1, 1); PG8_STAGE(PG8_SB(1, 0), b3, voffB); PG8_STAGE(PG8_SB(1, 1), b3 + hstepB, voffB); PG8_STAGE(PG8_SA(1, 0), a3, voffA);
;             PG8_WAIT_V(8); PG8_WAIT_L(0); PG8_BAR; PG8_MMA(1, 0, At, B0); PG8_MMA(1, 1, At, B1); PG8_BAR; PG8_SCHED;
	s_setprio 1
	s_waitcnt lgkmcnt(0)
	v_mfma_f32_16x16x32_bf16 v[124:127], v[128:131], v[188:191], v[124:127]
	v_mfma_f32_16x16x32_bf16 v[120:123], v[152:155], v[188:191], v[120:123]
	v_mfma_f32_16x16x32_bf16 v[108:111], v[128:131], v[196:199], v[108:111]
	v_mfma_f32_16x16x32_bf16 v[104:107], v[152:155], v[196:199], v[104:107]
	v_mfma_f32_16x16x32_bf16 v[92:95], v[128:131], v[204:207], v[92:95]
	v_mfma_f32_16x16x32_bf16 v[88:91], v[152:155], v[204:207], v[88:91]
	v_mfma_f32_16x16x32_bf16 v[76:79], v[128:131], v[212:215], v[76:79]
	v_mfma_f32_16x16x32_bf16 v[72:75], v[152:155], v[212:215], v[72:75]
	v_mfma_f32_16x16x32_bf16 v[124:127], v[132:135], v[192:195], v[124:127]
	v_mfma_f32_16x16x32_bf16 v[120:123], v[156:159], v[192:195], v[120:123]
	v_mfma_f32_16x16x32_bf16 v[108:111], v[132:135], v[200:203], v[108:111]
	v_mfma_f32_16x16x32_bf16 v[104:107], v[156:159], v[200:203], v[104:107]
	v_mfma_f32_16x16x32_bf16 v[92:95], v[132:135], v[208:211], v[92:95]
	v_mfma_f32_16x16x32_bf16 v[88:91], v[156:159], v[208:211], v[88:91]
	v_mfma_f32_16x16x32_bf16 v[76:79], v[132:135], v[216:219], v[76:79]
	v_mfma_f32_16x16x32_bf16 v[72:75], v[156:159], v[216:219], v[72:75]
	s_setprio 0
	s_setprio 1
	v_mfma_f32_16x16x32_bf16 v[116:119], v[160:163], v[188:191], v[116:119]
	v_mfma_f32_16x16x32_bf16 v[112:115], v[180:183], v[188:191], v[112:115]
	v_mfma_f32_16x16x32_bf16 v[100:103], v[160:163], v[196:199], v[100:103]
	v_mfma_f32_16x16x32_bf16 v[96:99], v[180:183], v[196:199], v[96:99]
	v_mfma_f32_16x16x32_bf16 v[84:87], v[160:163], v[204:207], v[84:87]
	v_mfma_f32_16x16x32_bf16 v[80:83], v[180:183], v[204:207], v[80:83]
	v_mfma_f32_16x16x32_bf16 v[68:71], v[160:163], v[212:215], v[68:71]
	v_mfma_f32_16x16x32_bf16 v[64:67], v[180:183], v[212:215], v[64:67]
	v_mfma_f32_16x16x32_bf16 v[116:119], v[164:167], v[192:195], v[116:119]
	v_mfma_f32_16x16x32_bf16 v[112:115], v[184:187], v[192:195], v[112:115]
	v_mfma_f32_16x16x32_bf16 v[100:103], v[164:167], v[200:203], v[100:103]
	v_mfma_f32_16x16x32_bf16 v[96:99], v[184:187], v[200:203], v[96:99]
	v_mfma_f32_16x16x32_bf16 v[84:87], v[164:167], v[208:211], v[84:87]
	v_mfma_f32_16x16x32_bf16 v[80:83], v[184:187], v[208:211], v[80:83]
	v_mfma_f32_16x16x32_bf16 v[68:71], v[164:167], v[216:219], v[68:71]
	v_mfma_f32_16x16x32_bf16 v[64:67], v[184:187], v[216:219], v[64:67]
	s_setprio 0
	s_barrier
	s_add_i32 s18, s69, s33
	v_lshl_add_u64 v[168:169], v[168:169], 0, s[30:31]
	s_mov_b32 m0, s18
	ds_read_b128 v[188:191], v175 offset:49152
	ds_read_b128 v[192:195], v175 offset:50176
	ds_read_b128 v[196:199], v175 offset:51200
	ds_read_b128 v[200:203], v175 offset:52224
	ds_read_b128 v[204:207], v175 offset:53248
	ds_read_b128 v[208:211], v175 offset:54272
	ds_read_b128 v[212:215], v175 offset:55296
	ds_read_b128 v[216:219], v175 offset:56320
	global_load_lds_dwordx4 v[168:169], off
	s_add_i32 m0, s18, 0x2000
	s_add_u32 s16, s16, 0x80080
	v_lshl_add_u64 v[168:169], v[220:221], 0, s[30:31]
	s_addc_u32 s17, s17, 0
	s_add_i32 s18, s70, s33
	global_load_lds_dwordx4 v[168:169], off
	v_lshl_add_u64 v[168:169], s[16:17], 0, v[138:139]
	s_mov_b32 m0, s18
	s_nop 0
	global_load_lds_dwordx4 v[168:169], off
	v_lshl_add_u64 v[168:169], s[16:17], 0, v[142:143]
	s_add_i32 m0, s18, 0x2000
	s_nop 0
	global_load_lds_dwordx4 v[168:169], off
	s_waitcnt vmcnt(6)
	s_waitcnt lgkmcnt(0)
	s_barrier
	s_setprio 1
	s_waitcnt lgkmcnt(0)
	v_mfma_f32_16x16x32_bf16 v[60:63], v[128:131], v[188:191], v[60:63]
	v_mfma_f32_16x16x32_bf16 v[56:59], v[152:155], v[188:191], v[56:59]
	v_mfma_f32_16x16x32_bf16 v[44:47], v[128:131], v[196:199], v[44:47]
	v_mfma_f32_16x16x32_bf16 v[40:43], v[152:155], v[196:199], v[40:43]
	v_mfma_f32_16x16x32_bf16 v[28:31], v[128:131], v[204:207], v[28:31]
	v_mfma_f32_16x16x32_bf16 v[24:27], v[152:155], v[204:207], v[24:27]
	v_mfma_f32_16x16x32_bf16 v[12:15], v[128:131], v[212:215], v[12:15]
	v_mfma_f32_16x16x32_bf16 v[8:11], v[152:155], v[212:215], v[8:11]
	v_mfma_f32_16x16x32_bf16 v[60:63], v[132:135], v[192:195], v[60:63]
	v_mfma_f32_16x16x32_bf16 v[56:59], v[156:159], v[192:195], v[56:59]
	v_mfma_f32_16x16x32_bf16 v[44:47], v[132:135], v[200:203], v[44:47]
	v_mfma_f32_16x16x32_bf16 v[40:43], v[156:159], v[200:203], v[40:43]
	v_mfma_f32_16x16x32_bf16 v[28:31], v[132:135], v[208:211], v[28:31]
	v_mfma_f32_16x16x32_bf16 v[24:27], v[156:159], v[208:211], v[24:27]
	v_mfma_f32_16x16x32_bf16 v[12:15], v[132:135], v[216:219], v[12:15]
	v_mfma_f32_16x16x32_bf16 v[8:11], v[156:159], v[216:219], v[8:11]
	s_setprio 0
	s_setprio 1
	v_mfma_f32_16x16x32_bf16 v[52:55], v[160:163], v[188:191], v[52:55]
	v_mfma_f32_16x16x32_bf16 v[48:51], v[180:183], v[188:191], v[48:51]
	v_mfma_f32_16x16x32_bf16 v[36:39], v[160:163], v[196:199], v[36:39]
	v_mfma_f32_16x16x32_bf16 v[32:35], v[180:183], v[196:199], v[32:35]
	v_mfma_f32_16x16x32_bf16 v[20:23], v[160:163], v[204:207], v[20:23]
	v_mfma_f32_16x16x32_bf16 v[16:19], v[180:183], v[204:207], v[16:19]
	v_mfma_f32_16x16x32_bf16 v[4:7], v[160:163], v[212:215], v[4:7]
	v_mfma_f32_16x16x32_bf16 v[0:3], v[180:183], v[212:215], v[0:3]
	v_mfma_f32_16x16x32_bf16 v[52:55], v[164:167], v[192:195], v[52:55]
	v_mfma_f32_16x16x32_bf16 v[48:51], v[184:187], v[192:195], v[48:51]
	v_mfma_f32_16x16x32_bf16 v[36:39], v[164:167], v[200:203], v[36:39]
	v_mfma_f32_16x16x32_bf16 v[32:35], v[184:187], v[200:203], v[32:35]
	v_mfma_f32_16x16x32_bf16 v[20:23], v[164:167], v[208:211], v[20:23]
	v_mfma_f32_16x16x32_bf16 v[16:19], v[184:187], v[208:211], v[16:19]
	v_mfma_f32_16x16x32_bf16 v[4:7], v[164:167], v[216:219], v[4:7]
	v_mfma_f32_16x16x32_bf16 v[0:3], v[184:187], v[216:219], v[0:3]
	s_setprio 0
	s_barrier
	s_add_i32 s61, s61, 2
	s_add_u32 s12, s12, 0x100
	s_addc_u32 s13, s13, 0
	s_add_u32 s37, s37, 0x100
	s_addc_u32 s60, s60, 0
	s_cmp_gt_u32 s61, 29
	s_cbranch_scc0 .LBB0_187
	s_and_b64 vcc, exec, s[96:97]
	s_cbranch_vccz .LBB0_190
	s_barrier

; #define PG8_STAGE(bufoff, gbase, voff) do { _Pragma("unroll") for (int _i = 0; _i < 2; ++_i) \
;         __builtin_amdgcn_global_load_lds((const unsigned*)((const char*)(gbase) + (voff)[_i]), (PG8_LAS unsigned*)(lds + (bufoff) + ldsw + _i * 8192), 16, 0, 0); } while (0)
; #define PG8_LDA(dst, b, h) do { _Pragma("unroll") for (int m = 0; m < 4; ++m) _Pragma("unroll") for (int k = 0; k < 2; ++k) dst[m][k] = *(const PG8_LAS bf16x8*)(lds + PG8_SA(b, h) + aoff + m * 2048 + k * 1024); } while (0)
; #define PG8_LDB(dst, b, h) do { _Pragma("unroll") for (int n = 0; n < 2; ++n) _Pragma("unroll") for (int k = 0; k < 2; ++k) dst[n][k] = *(const PG8_LAS bf16x8*)(lds + PG8_SB(b, h) + boff + n * 2048 + k * 1024); } while (0)
; #define PG8_MMA(ai, bj, At, Bt) do { __builtin_amdgcn_s_setprio(1); _Pragma("unroll") for (int m = 0; m < 4; ++m) _Pragma("unroll") for (int n = 0; n < 2; ++n) _Pragma("unroll") for (int k = 0; k < 2; ++k) \
;         acc[ai][bj][m][n] = __builtin_amdgcn_mfma_f32_16x16x32_bf16(Bt[n][k], At[m][k], acc[ai][bj][m][n], 0, 0, 0); __builtin_amdgcn_s_setprio(0); } while (0)
; template <class Epi, class Sched, bool ALIGN_EPI = false, bool SP2 = false>
; __device__ __forceinline__ void gemm_phase(PG8_LAS unsigned char* lds, const Gemm g, const Sched& S, const Epi& E) {
;     ...
;             if constexpr (SP2) {
;             PG8_LDB(B0, 0, 0); PG8_LDB(B1, 0, 1); PG8_SCHED; PG8_LDA(At, 0, 0); PG8_STAGE(PG8_SA(1, 1), a1 + hstepA, voffA);
;             PG8_WAIT_V(8); PG8_WAIT_L(0); PG8_BAR; PG8_MMA(0, 0, At, B0); PG8_MMA(0, 1, At, B1); PG8_BAR; PG8_SCHED;
;             PG8_LDA(At, 0, 1); PG8_STAGE(PG8_SB(0, 0), b2, voffB); PG8_STAGE(PG8_SB(0, 1), b2 + hstepB, voffB); PG8_STAGE(PG8_SA(0, 0), a2, voffA);
;             PG8_WAIT_V(8); PG8_WAIT_L(0); PG8_BAR; PG8_MMA(1, 0, At, B0); PG8_MMA(1, 1, At, B1); PG8_BAR; PG8_SCHED;
;             PG8_LDB(B0, 1, 0); PG8_LDB(B1, 1, 1); PG8_SCHED; PG8_LDA(At, 1, 0); PG8_STAGE(PG8_SA(0, 1), a2 + hstepA, voffA);
;             PG8_WAIT_V(8); PG8_WAIT_L(0); PG8_BAR; PG8_MMA(0, 0, At, B0); PG8_MMA(0, 1, At, B1); PG8_BAR; PG8_SCHED;
;             PG8_LDA(At, 1, 1); PG8_STAGE(PG8_SB(1, 0), b3, voffB); PG8_STAGE(PG8_SB(1, 1), b3 + hstepB, voffB); PG8_STAGE(PG8_SA(1, 0), a3, voffA);
;             PG8_WAIT_V(8); PG8_WAIT_L(0); PG8_BAR; PG8_MMA(1, 0, At, B0); PG8_MMA(1, 1, At, B1); PG8_BAR; PG8_SCHED;
.Lp7_full_loop:
.LBB0_1824:
	ds_read_b128 v[144:147], v151
	ds_read_b128 v[156:159], v151 offset:1024
	ds_read_b128 v[160:163], v151 offset:2048
	ds_read_b128 v[164:167], v151 offset:3072
	ds_read_b128 v[168:171], v152
	ds_read_b128 v[172:175], v152 offset:1024
	ds_read_b128 v[176:179], v152 offset:2048
	ds_read_b128 v[180:183], v152 offset:3072
	s_add_u32 s34, s30, 0xfff80080
	s_addc_u32 s35, s31, -1
	s_cmp_eq_u32 s62, 28
	s_cselect_b32 s39, s21, s35
	s_cselect_b32 s38, s25, s34
	s_cselect_b32 s35, s23, s61
	s_cselect_b32 s34, s59, s60
	v_lshl_add_u64 v[216:217], s[30:31], 0, v[136:137]
	s_add_i32 m0, s6, 0xc000
	ds_read_b128 v[184:187], v153
	ds_read_b128 v[188:191], v153 offset:1024
	ds_read_b128 v[192:195], v153 offset:2048
	ds_read_b128 v[196:199], v153 offset:3072
	ds_read_b128 v[200:203], v153 offset:4096
	ds_read_b128 v[204:207], v153 offset:5120
	ds_read_b128 v[208:211], v153 offset:6144
	ds_read_b128 v[212:215], v153 offset:7168
	s_add_u32 s98, s30, 0xfff80000
	s_addc_u32 s99, s31, -1
	s_mov_b32 m0, s46
	s_nop 0
	global_load_lds_dwordx4 v134, s[98:99]
	s_mov_b32 m0, s47
	s_nop 0
	global_load_lds_dwordx4 v130, s[98:99]
	s_add_i32 m0, s6, 0xc000
	s_nop 0
	global_load_lds_dwordx4 v[216:217], off
	v_lshl_add_u64 v[216:217], s[30:31], 0, v[138:139]
	s_add_i32 m0, s6, 0xe000
	s_nop 0
	global_load_lds_dwordx4 v[216:217], off
	s_waitcnt vmcnt(8)
	s_waitcnt lgkmcnt(0)
	s_barrier
	s_setprio 1
	s_waitcnt lgkmcnt(0)
	v_mfma_f32_16x16x32_bf16 v[124:127], v[144:147], v[184:187], v[124:127]
	v_mfma_f32_16x16x32_bf16 v[116:119], v[160:163], v[184:187], v[116:119]
	v_mfma_f32_16x16x32_bf16 v[108:111], v[144:147], v[192:195], v[108:111]
	v_mfma_f32_16x16x32_bf16 v[100:103], v[160:163], v[192:195], v[100:103]
	v_mfma_f32_16x16x32_bf16 v[92:95], v[144:147], v[200:203], v[92:95]
	v_mfma_f32_16x16x32_bf16 v[84:87], v[160:163], v[200:203], v[84:87]
	v_mfma_f32_16x16x32_bf16 v[76:79], v[144:147], v[208:211], v[76:79]
	v_mfma_f32_16x16x32_bf16 v[68:71], v[160:163], v[208:211], v[68:71]
	v_mfma_f32_16x16x32_bf16 v[124:127], v[156:159], v[188:191], v[124:127]
	v_mfma_f32_16x16x32_bf16 v[116:119], v[164:167], v[188:191], v[116:119]
	v_mfma_f32_16x16x32_bf16 v[108:111], v[156:159], v[196:199], v[108:111]
	v_mfma_f32_16x16x32_bf16 v[100:103], v[164:167], v[196:199], v[100:103]
	v_mfma_f32_16x16x32_bf16 v[92:95], v[156:159], v[204:207], v[92:95]
	v_mfma_f32_16x16x32_bf16 v[84:87], v[164:167], v[204:207], v[84:87]
	v_mfma_f32_16x16x32_bf16 v[76:79], v[156:159], v[212:215], v[76:79]
	v_mfma_f32_16x16x32_bf16 v[68:71], v[164:167], v[212:215], v[68:71]
	s_setprio 0
	s_setprio 1
	v_mfma_f32_16x16x32_bf16 v[120:123], v[168:171], v[184:187], v[120:123]
	v_mfma_f32_16x16x32_bf16 v[112:115], v[176:179], v[184:187], v[112:115]
	v_mfma_f32_16x16x32_bf16 v[104:107], v[168:171], v[192:195], v[104:107]
	v_mfma_f32_16x16x32_bf16 v[96:99], v[176:179], v[192:195], v[96:99]
	v_mfma_f32_16x16x32_bf16 v[88:91], v[168:171], v[200:203], v[88:91]
	v_mfma_f32_16x16x32_bf16 v[80:83], v[176:179], v[200:203], v[80:83]
	v_mfma_f32_16x16x32_bf16 v[72:75], v[168:171], v[208:211], v[72:75]
	v_mfma_f32_16x16x32_bf16 v[64:67], v[176:179], v[208:211], v[64:67]
	v_mfma_f32_16x16x32_bf16 v[120:123], v[172:175], v[188:191], v[120:123]
	v_mfma_f32_16x16x32_bf16 v[112:115], v[180:183], v[188:191], v[112:115]
	v_mfma_f32_16x16x32_bf16 v[104:107], v[172:175], v[196:199], v[104:107]
	v_mfma_f32_16x16x32_bf16 v[96:99], v[180:183], v[196:199], v[96:99]
	v_mfma_f32_16x16x32_bf16 v[88:91], v[172:175], v[204:207], v[88:91]
	v_mfma_f32_16x16x32_bf16 v[80:83], v[180:183], v[204:207], v[80:83]
	v_mfma_f32_16x16x32_bf16 v[72:75], v[172:175], v[212:215], v[72:75]
	v_mfma_f32_16x16x32_bf16 v[64:67], v[180:183], v[212:215], v[64:67]
	s_setprio 0
	s_barrier
	s_add_i32 s63, s53, s4
	v_lshl_add_u64 v[216:217], s[34:35], 0, v[132:133]
	s_mov_b32 m0, s63
	ds_read_b128 v[184:187], v153 offset:16384
	ds_read_b128 v[188:191], v153 offset:17408
	ds_read_b128 v[192:195], v153 offset:18432
	ds_read_b128 v[196:199], v153 offset:19456
	ds_read_b128 v[200:203], v153 offset:20480
	ds_read_b128 v[204:207], v153 offset:21504
	ds_read_b128 v[208:211], v153 offset:22528
	ds_read_b128 v[212:215], v153 offset:23552
	global_load_lds_dwordx4 v[216:217], off
	s_add_i32 m0, s63, 0x2000
	s_add_u32 s64, s34, 0x80000
	v_lshl_add_u64 v[218:219], s[34:35], 0, v[128:129]
	s_addc_u32 s65, s35, 0
	s_add_i32 s63, s54, s4
	global_load_lds_dwordx4 v[218:219], off
	v_lshl_add_u64 v[220:221], s[64:65], 0, v[132:133]
	s_mov_b32 m0, s63
	global_load_lds_dwordx4 v[220:221], off
	v_lshl_add_u64 v[220:221], s[64:65], 0, v[128:129]
	s_add_i32 m0, s63, 0x2000
	s_nop 0
	global_load_lds_dwordx4 v[220:221], off
	s_waitcnt vmcnt(6)
	s_waitcnt lgkmcnt(0)
	s_barrier
; #define PG8_STAGE(bufoff, gbase, voff) do { _Pragma("unroll") for (int _i = 0; _i < 2; ++_i) \
;         __builtin_amdgcn_global_load_lds((const unsigned*)((const char*)(gbase) + (voff)[_i]), (PG8_LAS unsigned*)(lds + (bufoff) + ldsw + _i * 8192), 16, 0, 0); } while (0)
; #define PG8_LDA(dst, b, h) do { _Pragma("unroll") for (int m = 0; m < 4; ++m) _Pragma("unroll") for (int k = 0; k < 2; ++k) dst[m][k] = *(const PG8_LAS bf16x8*)(lds + PG8_SA(b, h) + aoff + m * 2048 + k * 1024); } while (0)
; #define PG8_LDB(dst, b, h) do { _Pragma("unroll") for (int n = 0; n < 2; ++n) _Pragma("unroll") for (int k = 0; k < 2; ++k) dst[n][k] = *(const PG8_LAS bf16x8*)(lds + PG8_SB(b, h) + boff + n * 2048 + k * 1024); } while (0)
; #define PG8_MMA(ai, bj, At, Bt) do { __builtin_amdgcn_s_setprio(1); _Pragma("unroll") for (int m = 0; m < 4; ++m) _Pragma("unroll") for (int n = 0; n < 2; ++n) _Pragma("unroll") for (int k = 0; k < 2; ++k) \
;         acc[ai][bj][m][n] = __builtin_amdgcn_mfma_f32_16x16x32_bf16(Bt[n][k], At[m][k], acc[ai][bj][m][n], 0, 0, 0); __builtin_amdgcn_s_setprio(0); } while (0)
; template <class Epi, class Sched, bool ALIGN_EPI = false, bool SP2 = false>
; __device__ __forceinline__ void gemm_phase(PG8_LAS unsigned char* lds, const Gemm g, const Sched& S, const Epi& E) {
;     ...
;             if constexpr (SP2) {
;             PG8_LDB(B0, 0, 0); PG8_LDB(B1, 0, 1); PG8_SCHED; PG8_LDA(At, 0, 0); PG8_STAGE(PG8_SA(1, 1), a1 + hstepA, voffA);
;             PG8_WAIT_V(8); PG8_WAIT_L(0); PG8_BAR; PG8_MMA(0, 0, At, B0); PG8_MMA(0, 1, At, B1); PG8_BAR; PG8_SCHED;
;             PG8_LDA(At, 0, 1); PG8_STAGE(PG8_SB(0, 0), b2, voffB); PG8_STAGE(PG8_SB(0, 1), b2 + hstepB, voffB); PG8_STAGE(PG8_SA(0, 0), a2, voffA);
;             PG8_WAIT_V(8); PG8_WAIT_L(0); PG8_BAR; PG8_MMA(1, 0, At, B0); PG8_MMA(1, 1, At, B1); PG8_BAR; PG8_SCHED;
;             PG8_LDB(B0, 1, 0); PG8_LDB(B1, 1, 1); PG8_SCHED; PG8_LDA(At, 1, 0); PG8_STAGE(PG8_SA(0, 1), a2 + hstepA, voffA);
;             PG8_WAIT_V(8); PG8_WAIT_L(0); PG8_BAR; PG8_MMA(0, 0, At, B0); PG8_MMA(0, 1, At, B1); PG8_BAR; PG8_SCHED;
;             PG8_LDA(At, 1, 1); PG8_STAGE(PG8_SB(1, 0), b3, voffB); PG8_STAGE(PG8_SB(1, 1), b3 + hstepB, voffB); PG8_STAGE(PG8_SA(1, 0), a3, voffA);
;             PG8_WAIT_V(8); PG8_WAIT_L(0); PG8_BAR; PG8_MMA(1, 0, At, B0); PG8_MMA(1, 1, At, B1); PG8_BAR; PG8_SCHED;
	s_setprio 1
	s_waitcnt lgkmcnt(0)
	v_mfma_f32_16x16x32_bf16 v[60:63], v[144:147], v[184:187], v[60:63]
	v_mfma_f32_16x16x32_bf16 v[52:55], v[160:163], v[184:187], v[52:55]
	v_mfma_f32_16x16x32_bf16 v[44:47], v[144:147], v[192:195], v[44:47]
	v_mfma_f32_16x16x32_bf16 v[36:39], v[160:163], v[192:195], v[36:39]
	v_mfma_f32_16x16x32_bf16 v[28:31], v[144:147], v[200:203], v[28:31]
	v_mfma_f32_16x16x32_bf16 v[20:23], v[160:163], v[200:203], v[20:23]
	v_mfma_f32_16x16x32_bf16 v[12:15], v[144:147], v[208:211], v[12:15]
	v_mfma_f32_16x16x32_bf16 v[4:7], v[160:163], v[208:211], v[4:7]
	v_mfma_f32_16x16x32_bf16 v[60:63], v[156:159], v[188:191], v[60:63]
	v_mfma_f32_16x16x32_bf16 v[52:55], v[164:167], v[188:191], v[52:55]
	v_mfma_f32_16x16x32_bf16 v[44:47], v[156:159], v[196:199], v[44:47]
	v_mfma_f32_16x16x32_bf16 v[36:39], v[164:167], v[196:199], v[36:39]
	v_mfma_f32_16x16x32_bf16 v[28:31], v[156:159], v[204:207], v[28:31]
	v_mfma_f32_16x16x32_bf16 v[20:23], v[164:167], v[204:207], v[20:23]
	v_mfma_f32_16x16x32_bf16 v[12:15], v[156:159], v[212:215], v[12:15]
	v_mfma_f32_16x16x32_bf16 v[4:7], v[164:167], v[212:215], v[4:7]
	s_setprio 0
	s_setprio 1
	v_mfma_f32_16x16x32_bf16 v[56:59], v[168:171], v[184:187], v[56:59]
	v_mfma_f32_16x16x32_bf16 v[48:51], v[176:179], v[184:187], v[48:51]
	v_mfma_f32_16x16x32_bf16 v[40:43], v[168:171], v[192:195], v[40:43]
	v_mfma_f32_16x16x32_bf16 v[32:35], v[176:179], v[192:195], v[32:35]
	v_mfma_f32_16x16x32_bf16 v[24:27], v[168:171], v[200:203], v[24:27]
	v_mfma_f32_16x16x32_bf16 v[16:19], v[176:179], v[200:203], v[16:19]
	v_mfma_f32_16x16x32_bf16 v[8:11], v[168:171], v[208:211], v[8:11]
	v_mfma_f32_16x16x32_bf16 v[0:3], v[176:179], v[208:211], v[0:3]
	v_mfma_f32_16x16x32_bf16 v[56:59], v[172:175], v[188:191], v[56:59]
	v_mfma_f32_16x16x32_bf16 v[48:51], v[180:183], v[188:191], v[48:51]
	v_mfma_f32_16x16x32_bf16 v[40:43], v[172:175], v[196:199], v[40:43]
	v_mfma_f32_16x16x32_bf16 v[32:35], v[180:183], v[196:199], v[32:35]
	v_mfma_f32_16x16x32_bf16 v[24:27], v[172:175], v[204:207], v[24:27]
	v_mfma_f32_16x16x32_bf16 v[16:19], v[180:183], v[204:207], v[16:19]
	v_mfma_f32_16x16x32_bf16 v[8:11], v[172:175], v[212:215], v[8:11]
	v_mfma_f32_16x16x32_bf16 v[0:3], v[180:183], v[212:215], v[0:3]
	s_setprio 0
	s_barrier
	s_add_i32 s63, 0, 0x18000
	v_add_u32_e32 v155, s63, v150
	s_add_i32 s64, 0, 0x1c000
	ds_read_b128 v[144:147], v155
	ds_read_b128 v[156:159], v155 offset:1024
	ds_read_b128 v[160:163], v155 offset:2048
	ds_read_b128 v[164:167], v155 offset:3072
	v_add_u32_e32 v155, s64, v150
	ds_read_b128 v[168:171], v155
	ds_read_b128 v[172:175], v155 offset:1024
	ds_read_b128 v[176:179], v155 offset:2048
	ds_read_b128 v[180:183], v155 offset:3072
	s_mov_b64 s[100:101], s[38:39]
	s_add_u32 s38, s38, 0x80000
	s_addc_u32 s39, s39, 0
	s_mov_b32 m0, s41
	v_lshl_add_u64 v[224:225], s[38:39], 0, v[134:135]
	ds_read_b128 v[184:187], v153 offset:32768
	ds_read_b128 v[188:191], v153 offset:33792
	ds_read_b128 v[192:195], v153 offset:34816
	ds_read_b128 v[196:199], v153 offset:35840
	ds_read_b128 v[200:203], v153 offset:36864
	ds_read_b128 v[204:207], v153 offset:37888
	ds_read_b128 v[208:211], v153 offset:38912
	ds_read_b128 v[212:215], v153 offset:39936
	s_mov_b32 m0, s6
	s_nop 0
	global_load_lds_dwordx4 v134, s[100:101]
	s_mov_b32 m0, s7
	s_nop 0
	global_load_lds_dwordx4 v130, s[100:101]
	s_mov_b32 m0, s41
	s_nop 0
	global_load_lds_dwordx4 v[224:225], off
	v_lshl_add_u64 v[224:225], s[38:39], 0, v[130:131]
	s_mov_b32 m0, s42
	s_nop 0
	global_load_lds_dwordx4 v[224:225], off
	s_waitcnt vmcnt(8)
	s_waitcnt lgkmcnt(0)
	s_barrier
; #define PG8_STAGE(bufoff, gbase, voff) do { _Pragma("unroll") for (int _i = 0; _i < 2; ++_i) \
;         __builtin_amdgcn_global_load_lds((const unsigned*)((const char*)(gbase) + (voff)[_i]), (PG8_LAS unsigned*)(lds + (bufoff) + ldsw + _i * 8192), 16, 0, 0); } while (0)
; #define PG8_LDA(dst, b, h) do { _Pragma("unroll") for (int m = 0; m < 4; ++m) _Pragma("unroll") for (int k = 0; k < 2; ++k) dst[m][k] = *(const PG8_LAS bf16x8*)(lds + PG8_SA(b, h) + aoff + m * 2048 + k * 1024); } while (0)
; #define PG8_LDB(dst, b, h) do { _Pragma("unroll") for (int n = 0; n < 2; ++n) _Pragma("unroll") for (int k = 0; k < 2; ++k) dst[n][k] = *(const PG8_LAS bf16x8*)(lds + PG8_SB(b, h) + boff + n * 2048 + k * 1024); } while (0)
; #define PG8_MMA(ai, bj, At, Bt) do { __builtin_amdgcn_s_setprio(1); _Pragma("unroll") for (int m = 0; m < 4; ++m) _Pragma("unroll") for (int n = 0; n < 2; ++n) _Pragma("unroll") for (int k = 0; k < 2; ++k) \
;         acc[ai][bj][m][n] = __builtin_amdgcn_mfma_f32_16x16x32_bf16(Bt[n][k], At[m][k], acc[ai][bj][m][n], 0, 0, 0); __builtin_amdgcn_s_setprio(0); } while (0)
; template <class Epi, class Sched, bool ALIGN_EPI = false, bool SP2 = false>
; __device__ __forceinline__ void gemm_phase(PG8_LAS unsigned char* lds, const Gemm g, const Sched& S, const Epi& E) {
;     ...
;             if constexpr (SP2) {
;             PG8_LDB(B0, 0, 0); PG8_LDB(B1, 0, 1); PG8_SCHED; PG8_LDA(At, 0, 0); PG8_STAGE(PG8_SA(1, 1), a1 + hstepA, voffA);
;             PG8_WAIT_V(8); PG8_WAIT_L(0); PG8_BAR; PG8_MMA(0, 0, At, B0); PG8_MMA(0, 1, At, B1); PG8_BAR; PG8_SCHED;
;             PG8_LDA(At, 0, 1); PG8_STAGE(PG8_SB(0, 0), b2, voffB); PG8_STAGE(PG8_SB(0, 1), b2 + hstepB, voffB); PG8_STAGE(PG8_SA(0, 0), a2, voffA);
;             PG8_WAIT_V(8); PG8_WAIT_L(0); PG8_BAR; PG8_MMA(1, 0, At, B0); PG8_MMA(1, 1, At, B1); PG8_BAR; PG8_SCHED;
;             PG8_LDB(B0, 1, 0); PG8_LDB(B1, 1, 1); PG8_SCHED; PG8_LDA(At, 1, 0); PG8_STAGE(PG8_SA(0, 1), a2 + hstepA, voffA);
;             PG8_WAIT_V(8); PG8_WAIT_L(0); PG8_BAR; PG8_MMA(0, 0, At, B0); PG8_MMA(0, 1, At, B1); PG8_BAR; PG8_SCHED;
;             PG8_LDA(At, 1, 1); PG8_STAGE(PG8_SB(1, 0), b3, voffB); PG8_STAGE(PG8_SB(1, 1), b3 + hstepB, voffB); PG8_STAGE(PG8_SA(1, 0), a3, voffA);
;             PG8_WAIT_V(8); PG8_WAIT_L(0); PG8_BAR; PG8_MMA(1, 0, At, B0); PG8_MMA(1, 1, At, B1); PG8_BAR; PG8_SCHED;
	s_setprio 1
	s_waitcnt lgkmcnt(0)
	v_mfma_f32_16x16x32_bf16 v[124:127], v[144:147], v[184:187], v[124:127]
	v_mfma_f32_16x16x32_bf16 v[116:119], v[160:163], v[184:187], v[116:119]
	v_mfma_f32_16x16x32_bf16 v[108:111], v[144:147], v[192:195], v[108:111]
	v_mfma_f32_16x16x32_bf16 v[100:103], v[160:163], v[192:195], v[100:103]
	v_mfma_f32_16x16x32_bf16 v[92:95], v[144:147], v[200:203], v[92:95]
	v_mfma_f32_16x16x32_bf16 v[84:87], v[160:163], v[200:203], v[84:87]
	v_mfma_f32_16x16x32_bf16 v[76:79], v[144:147], v[208:211], v[76:79]
	v_mfma_f32_16x16x32_bf16 v[68:71], v[160:163], v[208:211], v[68:71]
	v_mfma_f32_16x16x32_bf16 v[124:127], v[156:159], v[188:191], v[124:127]
	v_mfma_f32_16x16x32_bf16 v[116:119], v[164:167], v[188:191], v[116:119]
	v_mfma_f32_16x16x32_bf16 v[108:111], v[156:159], v[196:199], v[108:111]
	v_mfma_f32_16x16x32_bf16 v[100:103], v[164:167], v[196:199], v[100:103]
	v_mfma_f32_16x16x32_bf16 v[92:95], v[156:159], v[204:207], v[92:95]
	v_mfma_f32_16x16x32_bf16 v[84:87], v[164:167], v[204:207], v[84:87]
	v_mfma_f32_16x16x32_bf16 v[76:79], v[156:159], v[212:215], v[76:79]
	v_mfma_f32_16x16x32_bf16 v[68:71], v[164:167], v[212:215], v[68:71]
	s_setprio 0
	s_setprio 1
	v_mfma_f32_16x16x32_bf16 v[120:123], v[168:171], v[184:187], v[120:123]
	v_mfma_f32_16x16x32_bf16 v[112:115], v[176:179], v[184:187], v[112:115]
	v_mfma_f32_16x16x32_bf16 v[104:107], v[168:171], v[192:195], v[104:107]
	v_mfma_f32_16x16x32_bf16 v[96:99], v[176:179], v[192:195], v[96:99]
	v_mfma_f32_16x16x32_bf16 v[88:91], v[168:171], v[200:203], v[88:91]
	v_mfma_f32_16x16x32_bf16 v[80:83], v[176:179], v[200:203], v[80:83]
	v_mfma_f32_16x16x32_bf16 v[72:75], v[168:171], v[208:211], v[72:75]
	v_mfma_f32_16x16x32_bf16 v[64:67], v[176:179], v[208:211], v[64:67]
	v_mfma_f32_16x16x32_bf16 v[120:123], v[172:175], v[188:191], v[120:123]
	v_mfma_f32_16x16x32_bf16 v[112:115], v[180:183], v[188:191], v[112:115]
	v_mfma_f32_16x16x32_bf16 v[104:107], v[172:175], v[196:199], v[104:107]
	v_mfma_f32_16x16x32_bf16 v[96:99], v[180:183], v[196:199], v[96:99]
	v_mfma_f32_16x16x32_bf16 v[88:91], v[172:175], v[204:207], v[88:91]
	v_mfma_f32_16x16x32_bf16 v[80:83], v[180:183], v[204:207], v[80:83]
	v_mfma_f32_16x16x32_bf16 v[72:75], v[172:175], v[212:215], v[72:75]
	v_mfma_f32_16x16x32_bf16 v[64:67], v[180:183], v[212:215], v[64:67]
	s_setprio 0
	s_barrier
	s_add_i32 s38, s63, s4
	v_lshl_add_u64 v[216:217], v[216:217], 0, s[16:17]
	s_mov_b32 m0, s38
	ds_read_b128 v[184:187], v153 offset:49152
	ds_read_b128 v[188:191], v153 offset:50176
	ds_read_b128 v[192:195], v153 offset:51200
	ds_read_b128 v[196:199], v153 offset:52224
	ds_read_b128 v[200:203], v153 offset:53248
	ds_read_b128 v[204:207], v153 offset:54272
	ds_read_b128 v[208:211], v153 offset:55296
	ds_read_b128 v[212:215], v153 offset:56320
	global_load_lds_dwordx4 v[216:217], off
	s_add_i32 m0, s38, 0x2000
	s_add_u32 s34, s34, 0x80080
	v_lshl_add_u64 v[216:217], v[218:219], 0, s[16:17]
	s_addc_u32 s35, s35, 0
	s_add_i32 s38, s64, s4
	global_load_lds_dwordx4 v[216:217], off
	v_lshl_add_u64 v[216:217], s[34:35], 0, v[132:133]
	s_mov_b32 m0, s38
	s_nop 0
	global_load_lds_dwordx4 v[216:217], off
	v_lshl_add_u64 v[216:217], s[34:35], 0, v[128:129]
	s_add_i32 m0, s38, 0x2000
	s_nop 0
	global_load_lds_dwordx4 v[216:217], off
	s_waitcnt vmcnt(6)
	s_waitcnt lgkmcnt(0)
	s_barrier
	s_setprio 1
	s_waitcnt lgkmcnt(0)
	v_mfma_f32_16x16x32_bf16 v[60:63], v[144:147], v[184:187], v[60:63]
	v_mfma_f32_16x16x32_bf16 v[52:55], v[160:163], v[184:187], v[52:55]
	v_mfma_f32_16x16x32_bf16 v[44:47], v[144:147], v[192:195], v[44:47]
	v_mfma_f32_16x16x32_bf16 v[36:39], v[160:163], v[192:195], v[36:39]
	v_mfma_f32_16x16x32_bf16 v[28:31], v[144:147], v[200:203], v[28:31]
	v_mfma_f32_16x16x32_bf16 v[20:23], v[160:163], v[200:203], v[20:23]
	v_mfma_f32_16x16x32_bf16 v[12:15], v[144:147], v[208:211], v[12:15]
	v_mfma_f32_16x16x32_bf16 v[4:7], v[160:163], v[208:211], v[4:7]
	v_mfma_f32_16x16x32_bf16 v[60:63], v[156:159], v[188:191], v[60:63]
	v_mfma_f32_16x16x32_bf16 v[52:55], v[164:167], v[188:191], v[52:55]
	v_mfma_f32_16x16x32_bf16 v[44:47], v[156:159], v[196:199], v[44:47]
	v_mfma_f32_16x16x32_bf16 v[36:39], v[164:167], v[196:199], v[36:39]
	v_mfma_f32_16x16x32_bf16 v[28:31], v[156:159], v[204:207], v[28:31]
	v_mfma_f32_16x16x32_bf16 v[20:23], v[164:167], v[204:207], v[20:23]
	v_mfma_f32_16x16x32_bf16 v[12:15], v[156:159], v[212:215], v[12:15]
	v_mfma_f32_16x16x32_bf16 v[4:7], v[164:167], v[212:215], v[4:7]
	s_setprio 0
	s_setprio 1
	v_mfma_f32_16x16x32_bf16 v[56:59], v[168:171], v[184:187], v[56:59]
	v_mfma_f32_16x16x32_bf16 v[48:51], v[176:179], v[184:187], v[48:51]
	v_mfma_f32_16x16x32_bf16 v[40:43], v[168:171], v[192:195], v[40:43]
	v_mfma_f32_16x16x32_bf16 v[32:35], v[176:179], v[192:195], v[32:35]
	v_mfma_f32_16x16x32_bf16 v[24:27], v[168:171], v[200:203], v[24:27]
	v_mfma_f32_16x16x32_bf16 v[16:19], v[176:179], v[200:203], v[16:19]
	v_mfma_f32_16x16x32_bf16 v[8:11], v[168:171], v[208:211], v[8:11]
	v_mfma_f32_16x16x32_bf16 v[0:3], v[176:179], v[208:211], v[0:3]
	v_mfma_f32_16x16x32_bf16 v[56:59], v[172:175], v[188:191], v[56:59]
	v_mfma_f32_16x16x32_bf16 v[48:51], v[180:183], v[188:191], v[48:51]
	v_mfma_f32_16x16x32_bf16 v[40:43], v[172:175], v[196:199], v[40:43]
	v_mfma_f32_16x16x32_bf16 v[32:35], v[180:183], v[196:199], v[32:35]
	v_mfma_f32_16x16x32_bf16 v[24:27], v[172:175], v[204:207], v[24:27]
	v_mfma_f32_16x16x32_bf16 v[16:19], v[180:183], v[204:207], v[16:19]
	v_mfma_f32_16x16x32_bf16 v[8:11], v[172:175], v[212:215], v[8:11]
	v_mfma_f32_16x16x32_bf16 v[0:3], v[180:183], v[212:215], v[0:3]
	s_setprio 0
	s_barrier
	s_add_i32 s62, s62, 2
	s_add_u32 s30, s30, 0x100
	s_addc_u32 s31, s31, 0
	s_add_u32 s60, s60, 0x100
	s_addc_u32 s61, s61, 0
	s_cmp_gt_u32 s62, 29
	s_cbranch_scc0 .LBB0_1824

; #define PG8_STAGE(bufoff, gbase, voff) do { _Pragma("unroll") for (int _i = 0; _i < 2; ++_i) \
;         __builtin_amdgcn_global_load_lds((const unsigned*)((const char*)(gbase) + (voff)[_i]), (PG8_LAS unsigned*)(lds + (bufoff) + ldsw + _i * 8192), 16, 0, 0); } while (0)
; #define PG8_LDA(dst, b, h) do { _Pragma("unroll") for (int m = 0; m < 4; ++m) _Pragma("unroll") for (int k = 0; k < 2; ++k) dst[m][k] = *(const PG8_LAS bf16x8*)(lds + PG8_SA(b, h) + aoff + m * 2048 + k * 1024); } while (0)
; #define PG8_LDB(dst, b, h) do { _Pragma("unroll") for (int n = 0; n < 2; ++n) _Pragma("unroll") for (int k = 0; k < 2; ++k) dst[n][k] = *(const PG8_LAS bf16x8*)(lds + PG8_SB(b, h) + boff + n * 2048 + k * 1024); } while (0)
; #define PG8_MMA(ai, bj, At, Bt) do { __builtin_amdgcn_s_setprio(1); _Pragma("unroll") for (int m = 0; m < 4; ++m) _Pragma("unroll") for (int n = 0; n < 2; ++n) _Pragma("unroll") for (int k = 0; k < 2; ++k) \
;         acc[ai][bj][m][n] = __builtin_amdgcn_mfma_f32_16x16x32_bf16(Bt[n][k], At[m][k], acc[ai][bj][m][n], 0, 0, 0); __builtin_amdgcn_s_setprio(0); } while (0)
; template <class Epi, class Sched, bool ALIGN_EPI = false, bool SP2 = false>
; __device__ __forceinline__ void gemm_phase(PG8_LAS unsigned char* lds, const Gemm g, const Sched& S, const Epi& E) {
;     ...
;             if constexpr (SP2) {
;             PG8_LDB(B0, 0, 0); PG8_LDB(B1, 0, 1); PG8_SCHED; PG8_LDA(At, 0, 0); PG8_STAGE(PG8_SA(1, 1), a1 + hstepA, voffA);
;             PG8_WAIT_V(8); PG8_WAIT_L(0); PG8_BAR; PG8_MMA(0, 0, At, B0); PG8_MMA(0, 1, At, B1); PG8_BAR; PG8_SCHED;
;             PG8_LDA(At, 0, 1); PG8_STAGE(PG8_SB(0, 0), b2, voffB); PG8_STAGE(PG8_SB(0, 1), b2 + hstepB, voffB); PG8_STAGE(PG8_SA(0, 0), a2, voffA);
;             PG8_WAIT_V(8); PG8_WAIT_L(0); PG8_BAR; PG8_MMA(1, 0, At, B0); PG8_MMA(1, 1, At, B1); PG8_BAR; PG8_SCHED;
;             PG8_LDB(B0, 1, 0); PG8_LDB(B1, 1, 1); PG8_SCHED; PG8_LDA(At, 1, 0); PG8_STAGE(PG8_SA(0, 1), a2 + hstepA, voffA);
;             PG8_WAIT_V(8); PG8_WAIT_L(0); PG8_BAR; PG8_MMA(0, 0, At, B0); PG8_MMA(0, 1, At, B1); PG8_BAR; PG8_SCHED;
;             PG8_LDA(At, 1, 1); PG8_STAGE(PG8_SB(1, 0), b3, voffB); PG8_STAGE(PG8_SB(1, 1), b3 + hstepB, voffB); PG8_STAGE(PG8_SA(1, 0), a3, voffA);
;             PG8_WAIT_V(8); PG8_WAIT_L(0); PG8_BAR; PG8_MMA(1, 0, At, B0); PG8_MMA(1, 1, At, B1); PG8_BAR; PG8_SCHED;
.LBB0_1912:
	ds_read_b128 v[144:147], v151
	ds_read_b128 v[154:157], v151 offset:1024
	ds_read_b128 v[158:161], v151 offset:2048
	ds_read_b128 v[162:165], v151 offset:3072
	ds_read_b128 v[166:169], v152
	ds_read_b128 v[170:173], v152 offset:1024
	ds_read_b128 v[174:177], v152 offset:2048
	ds_read_b128 v[178:181], v152 offset:3072
	s_add_u32 s4, s40, 0x100
	s_addc_u32 s5, s41, 0
	s_cmpk_eq_i32 s65, 0x54
	s_cselect_b32 s47, s35, s5
	s_cselect_b32 s46, s34, s4
	s_cselect_b32 s43, s37, s64
	s_cselect_b32 s42, s36, s39
	v_lshl_add_u64 v[214:215], s[40:41], 0, v[136:137]
	s_add_i32 m0, s50, 0xc000
	ds_read_b128 v[182:185], v153
	ds_read_b128 v[186:189], v153 offset:1024
	ds_read_b128 v[190:193], v153 offset:2048
	ds_read_b128 v[194:197], v153 offset:3072
	ds_read_b128 v[198:201], v153 offset:4096
	ds_read_b128 v[202:205], v153 offset:5120
	ds_read_b128 v[206:209], v153 offset:6144
	ds_read_b128 v[210:213], v153 offset:7168
	s_add_u32 s98, s40, 0x80
	s_addc_u32 s99, s41, 0
	s_mov_b32 m0, s55
	s_nop 0
	global_load_lds_dwordx4 v128, s[98:99]
	s_mov_b32 m0, s56
	s_nop 0
	global_load_lds_dwordx4 v132, s[98:99]
	s_add_i32 m0, s50, 0xc000
	s_nop 0
	global_load_lds_dwordx4 v[214:215], off
	v_lshl_add_u64 v[214:215], s[40:41], 0, v[138:139]
	s_add_i32 m0, s50, 0xe000
	s_nop 0
	global_load_lds_dwordx4 v[214:215], off
	s_waitcnt vmcnt(8)
	s_waitcnt lgkmcnt(0)
	s_barrier
	s_setprio 1
	s_waitcnt lgkmcnt(0)
	v_mfma_f32_16x16x32_bf16 v[120:123], v[144:147], v[182:185], v[120:123]
	v_mfma_f32_16x16x32_bf16 v[124:127], v[158:161], v[182:185], v[124:127]
	v_mfma_f32_16x16x32_bf16 v[104:107], v[144:147], v[190:193], v[104:107]
	v_mfma_f32_16x16x32_bf16 v[108:111], v[158:161], v[190:193], v[108:111]
	v_mfma_f32_16x16x32_bf16 v[88:91], v[144:147], v[198:201], v[88:91]
	v_mfma_f32_16x16x32_bf16 v[92:95], v[158:161], v[198:201], v[92:95]
	v_mfma_f32_16x16x32_bf16 v[72:75], v[144:147], v[206:209], v[72:75]
	v_mfma_f32_16x16x32_bf16 v[76:79], v[158:161], v[206:209], v[76:79]
	v_mfma_f32_16x16x32_bf16 v[120:123], v[154:157], v[186:189], v[120:123]
	v_mfma_f32_16x16x32_bf16 v[124:127], v[162:165], v[186:189], v[124:127]
	v_mfma_f32_16x16x32_bf16 v[104:107], v[154:157], v[194:197], v[104:107]
	v_mfma_f32_16x16x32_bf16 v[108:111], v[162:165], v[194:197], v[108:111]
	v_mfma_f32_16x16x32_bf16 v[88:91], v[154:157], v[202:205], v[88:91]
	v_mfma_f32_16x16x32_bf16 v[92:95], v[162:165], v[202:205], v[92:95]
	v_mfma_f32_16x16x32_bf16 v[72:75], v[154:157], v[210:213], v[72:75]
	v_mfma_f32_16x16x32_bf16 v[76:79], v[162:165], v[210:213], v[76:79]
	s_setprio 0
	s_setprio 1
	v_mfma_f32_16x16x32_bf16 v[112:115], v[166:169], v[182:185], v[112:115]
	v_mfma_f32_16x16x32_bf16 v[116:119], v[174:177], v[182:185], v[116:119]
	v_mfma_f32_16x16x32_bf16 v[96:99], v[166:169], v[190:193], v[96:99]
	v_mfma_f32_16x16x32_bf16 v[100:103], v[174:177], v[190:193], v[100:103]
	v_mfma_f32_16x16x32_bf16 v[80:83], v[166:169], v[198:201], v[80:83]
	v_mfma_f32_16x16x32_bf16 v[84:87], v[174:177], v[198:201], v[84:87]
	v_mfma_f32_16x16x32_bf16 v[64:67], v[166:169], v[206:209], v[64:67]
	v_mfma_f32_16x16x32_bf16 v[68:71], v[174:177], v[206:209], v[68:71]
	v_mfma_f32_16x16x32_bf16 v[112:115], v[170:173], v[186:189], v[112:115]
	v_mfma_f32_16x16x32_bf16 v[116:119], v[178:181], v[186:189], v[116:119]
	v_mfma_f32_16x16x32_bf16 v[96:99], v[170:173], v[194:197], v[96:99]
	v_mfma_f32_16x16x32_bf16 v[100:103], v[178:181], v[194:197], v[100:103]
	v_mfma_f32_16x16x32_bf16 v[80:83], v[170:173], v[202:205], v[80:83]
	v_mfma_f32_16x16x32_bf16 v[84:87], v[178:181], v[202:205], v[84:87]
	v_mfma_f32_16x16x32_bf16 v[64:67], v[170:173], v[210:213], v[64:67]
	v_mfma_f32_16x16x32_bf16 v[68:71], v[178:181], v[210:213], v[68:71]
	s_setprio 0
	s_barrier
	s_add_i32 s40, s58, s33
	v_lshl_add_u64 v[214:215], s[42:43], 0, v[130:131]
	s_mov_b32 m0, s40
	ds_read_b128 v[182:185], v153 offset:16384
	ds_read_b128 v[186:189], v153 offset:17408
	ds_read_b128 v[190:193], v153 offset:18432
	ds_read_b128 v[194:197], v153 offset:19456
	ds_read_b128 v[198:201], v153 offset:20480
	ds_read_b128 v[202:205], v153 offset:21504
	ds_read_b128 v[206:209], v153 offset:22528
	ds_read_b128 v[210:213], v153 offset:23552
	global_load_lds_dwordx4 v[214:215], off
	s_add_i32 m0, s40, 0x2000
	s_add_u32 s40, s42, 0x160000
	v_lshl_add_u64 v[216:217], s[42:43], 0, v[134:135]
	s_addc_u32 s41, s43, 0
	s_add_i32 s66, s59, s33
	global_load_lds_dwordx4 v[216:217], off
	v_lshl_add_u64 v[218:219], s[40:41], 0, v[130:131]
	s_mov_b32 m0, s66
	global_load_lds_dwordx4 v[218:219], off
	v_lshl_add_u64 v[218:219], s[40:41], 0, v[134:135]
	s_add_i32 m0, s66, 0x2000
	s_nop 0
	global_load_lds_dwordx4 v[218:219], off
	s_waitcnt vmcnt(6)
	s_waitcnt lgkmcnt(0)
	s_barrier
; #define PG8_STAGE(bufoff, gbase, voff) do { _Pragma("unroll") for (int _i = 0; _i < 2; ++_i) \
;         __builtin_amdgcn_global_load_lds((const unsigned*)((const char*)(gbase) + (voff)[_i]), (PG8_LAS unsigned*)(lds + (bufoff) + ldsw + _i * 8192), 16, 0, 0); } while (0)
; #define PG8_LDA(dst, b, h) do { _Pragma("unroll") for (int m = 0; m < 4; ++m) _Pragma("unroll") for (int k = 0; k < 2; ++k) dst[m][k] = *(const PG8_LAS bf16x8*)(lds + PG8_SA(b, h) + aoff + m * 2048 + k * 1024); } while (0)
; #define PG8_LDB(dst, b, h) do { _Pragma("unroll") for (int n = 0; n < 2; ++n) _Pragma("unroll") for (int k = 0; k < 2; ++k) dst[n][k] = *(const PG8_LAS bf16x8*)(lds + PG8_SB(b, h) + boff + n * 2048 + k * 1024); } while (0)
; #define PG8_MMA(ai, bj, At, Bt) do { __builtin_amdgcn_s_setprio(1); _Pragma("unroll") for (int m = 0; m < 4; ++m) _Pragma("unroll") for (int n = 0; n < 2; ++n) _Pragma("unroll") for (int k = 0; k < 2; ++k) \
;         acc[ai][bj][m][n] = __builtin_amdgcn_mfma_f32_16x16x32_bf16(Bt[n][k], At[m][k], acc[ai][bj][m][n], 0, 0, 0); __builtin_amdgcn_s_setprio(0); } while (0)
; template <class Epi, class Sched, bool ALIGN_EPI = false, bool SP2 = false>
; __device__ __forceinline__ void gemm_phase(PG8_LAS unsigned char* lds, const Gemm g, const Sched& S, const Epi& E) {
;     ...
;             if constexpr (SP2) {
;             PG8_LDB(B0, 0, 0); PG8_LDB(B1, 0, 1); PG8_SCHED; PG8_LDA(At, 0, 0); PG8_STAGE(PG8_SA(1, 1), a1 + hstepA, voffA);
;             PG8_WAIT_V(8); PG8_WAIT_L(0); PG8_BAR; PG8_MMA(0, 0, At, B0); PG8_MMA(0, 1, At, B1); PG8_BAR; PG8_SCHED;
;             PG8_LDA(At, 0, 1); PG8_STAGE(PG8_SB(0, 0), b2, voffB); PG8_STAGE(PG8_SB(0, 1), b2 + hstepB, voffB); PG8_STAGE(PG8_SA(0, 0), a2, voffA);
;             PG8_WAIT_V(8); PG8_WAIT_L(0); PG8_BAR; PG8_MMA(1, 0, At, B0); PG8_MMA(1, 1, At, B1); PG8_BAR; PG8_SCHED;
;             PG8_LDB(B0, 1, 0); PG8_LDB(B1, 1, 1); PG8_SCHED; PG8_LDA(At, 1, 0); PG8_STAGE(PG8_SA(0, 1), a2 + hstepA, voffA);
;             PG8_WAIT_V(8); PG8_WAIT_L(0); PG8_BAR; PG8_MMA(0, 0, At, B0); PG8_MMA(0, 1, At, B1); PG8_BAR; PG8_SCHED;
;             PG8_LDA(At, 1, 1); PG8_STAGE(PG8_SB(1, 0), b3, voffB); PG8_STAGE(PG8_SB(1, 1), b3 + hstepB, voffB); PG8_STAGE(PG8_SA(1, 0), a3, voffA);
;             PG8_WAIT_V(8); PG8_WAIT_L(0); PG8_BAR; PG8_MMA(1, 0, At, B0); PG8_MMA(1, 1, At, B1); PG8_BAR; PG8_SCHED;
	s_setprio 1
	s_waitcnt lgkmcnt(0)
	v_mfma_f32_16x16x32_bf16 v[56:59], v[144:147], v[182:185], v[56:59]
	v_mfma_f32_16x16x32_bf16 v[60:63], v[158:161], v[182:185], v[60:63]
	v_mfma_f32_16x16x32_bf16 v[40:43], v[144:147], v[190:193], v[40:43]
	v_mfma_f32_16x16x32_bf16 v[44:47], v[158:161], v[190:193], v[44:47]
	v_mfma_f32_16x16x32_bf16 v[24:27], v[144:147], v[198:201], v[24:27]
	v_mfma_f32_16x16x32_bf16 v[28:31], v[158:161], v[198:201], v[28:31]
	v_mfma_f32_16x16x32_bf16 v[8:11], v[144:147], v[206:209], v[8:11]
	v_mfma_f32_16x16x32_bf16 v[12:15], v[158:161], v[206:209], v[12:15]
	v_mfma_f32_16x16x32_bf16 v[56:59], v[154:157], v[186:189], v[56:59]
	v_mfma_f32_16x16x32_bf16 v[60:63], v[162:165], v[186:189], v[60:63]
	v_mfma_f32_16x16x32_bf16 v[40:43], v[154:157], v[194:197], v[40:43]
	v_mfma_f32_16x16x32_bf16 v[44:47], v[162:165], v[194:197], v[44:47]
	v_mfma_f32_16x16x32_bf16 v[24:27], v[154:157], v[202:205], v[24:27]
	v_mfma_f32_16x16x32_bf16 v[28:31], v[162:165], v[202:205], v[28:31]
	v_mfma_f32_16x16x32_bf16 v[8:11], v[154:157], v[210:213], v[8:11]
	v_mfma_f32_16x16x32_bf16 v[12:15], v[162:165], v[210:213], v[12:15]
	s_setprio 0
	s_setprio 1
	v_mfma_f32_16x16x32_bf16 v[48:51], v[166:169], v[182:185], v[48:51]
	v_mfma_f32_16x16x32_bf16 v[52:55], v[174:177], v[182:185], v[52:55]
	v_mfma_f32_16x16x32_bf16 v[32:35], v[166:169], v[190:193], v[32:35]
	v_mfma_f32_16x16x32_bf16 v[36:39], v[174:177], v[190:193], v[36:39]
	v_mfma_f32_16x16x32_bf16 v[16:19], v[166:169], v[198:201], v[16:19]
	v_mfma_f32_16x16x32_bf16 v[20:23], v[174:177], v[198:201], v[20:23]
	v_mfma_f32_16x16x32_bf16 v[4:7], v[166:169], v[206:209], v[4:7]
	v_mfma_f32_16x16x32_bf16 v[0:3], v[174:177], v[206:209], v[0:3]
	v_mfma_f32_16x16x32_bf16 v[48:51], v[170:173], v[186:189], v[48:51]
	v_mfma_f32_16x16x32_bf16 v[52:55], v[178:181], v[186:189], v[52:55]
	v_mfma_f32_16x16x32_bf16 v[32:35], v[170:173], v[194:197], v[32:35]
	v_mfma_f32_16x16x32_bf16 v[36:39], v[178:181], v[194:197], v[36:39]
	v_mfma_f32_16x16x32_bf16 v[16:19], v[170:173], v[202:205], v[16:19]
	v_mfma_f32_16x16x32_bf16 v[20:23], v[178:181], v[202:205], v[20:23]
	v_mfma_f32_16x16x32_bf16 v[4:7], v[170:173], v[210:213], v[4:7]
	v_mfma_f32_16x16x32_bf16 v[0:3], v[178:181], v[210:213], v[0:3]
	s_setprio 0
	s_barrier
	s_add_i32 s66, 0, 0x18000
	s_add_i32 s67, 0, 0x1c000
	v_add_u32_e32 v162, s66, v150
	v_add_u32_e32 v178, s67, v150
	ds_read_b128 v[144:147], v162
	ds_read_b128 v[154:157], v162 offset:1024
	ds_read_b128 v[158:161], v162 offset:2048
	ds_read_b128 v[162:165], v162 offset:3072
	ds_read_b128 v[166:169], v178
	ds_read_b128 v[170:173], v178 offset:1024
	ds_read_b128 v[174:177], v178 offset:2048
	ds_read_b128 v[178:181], v178 offset:3072
	s_add_u32 s40, s46, 0x160000
	s_addc_u32 s41, s47, 0
	s_mov_b32 m0, s52
	v_lshl_add_u64 v[222:223], s[40:41], 0, v[128:129]
	ds_read_b128 v[182:185], v153 offset:32768
	ds_read_b128 v[186:189], v153 offset:33792
	ds_read_b128 v[190:193], v153 offset:34816
	ds_read_b128 v[194:197], v153 offset:35840
	ds_read_b128 v[198:201], v153 offset:36864
	ds_read_b128 v[202:205], v153 offset:37888
	ds_read_b128 v[206:209], v153 offset:38912
	ds_read_b128 v[210:213], v153 offset:39936
	s_mov_b32 m0, s50
	s_nop 0
	global_load_lds_dwordx4 v128, s[46:47]
	s_mov_b32 m0, s51
	s_nop 0
	global_load_lds_dwordx4 v132, s[46:47]
	s_mov_b32 m0, s52
	s_nop 0
	global_load_lds_dwordx4 v[222:223], off
	v_lshl_add_u64 v[222:223], s[40:41], 0, v[132:133]
	s_mov_b32 m0, s53
	s_nop 0
	global_load_lds_dwordx4 v[222:223], off
	s_waitcnt vmcnt(8)
	s_waitcnt lgkmcnt(0)
	s_barrier
; #define PG8_STAGE(bufoff, gbase, voff) do { _Pragma("unroll") for (int _i = 0; _i < 2; ++_i) \
;         __builtin_amdgcn_global_load_lds((const unsigned*)((const char*)(gbase) + (voff)[_i]), (PG8_LAS unsigned*)(lds + (bufoff) + ldsw + _i * 8192), 16, 0, 0); } while (0)
; #define PG8_LDA(dst, b, h) do { _Pragma("unroll") for (int m = 0; m < 4; ++m) _Pragma("unroll") for (int k = 0; k < 2; ++k) dst[m][k] = *(const PG8_LAS bf16x8*)(lds + PG8_SA(b, h) + aoff + m * 2048 + k * 1024); } while (0)
; #define PG8_LDB(dst, b, h) do { _Pragma("unroll") for (int n = 0; n < 2; ++n) _Pragma("unroll") for (int k = 0; k < 2; ++k) dst[n][k] = *(const PG8_LAS bf16x8*)(lds + PG8_SB(b, h) + boff + n * 2048 + k * 1024); } while (0)
; #define PG8_MMA(ai, bj, At, Bt) do { __builtin_amdgcn_s_setprio(1); _Pragma("unroll") for (int m = 0; m < 4; ++m) _Pragma("unroll") for (int n = 0; n < 2; ++n) _Pragma("unroll") for (int k = 0; k < 2; ++k) \
;         acc[ai][bj][m][n] = __builtin_amdgcn_mfma_f32_16x16x32_bf16(Bt[n][k], At[m][k], acc[ai][bj][m][n], 0, 0, 0); __builtin_amdgcn_s_setprio(0); } while (0)
; template <class Epi, class Sched, bool ALIGN_EPI = false, bool SP2 = false>
; __device__ __forceinline__ void gemm_phase(PG8_LAS unsigned char* lds, const Gemm g, const Sched& S, const Epi& E) {
;     ...
;             if constexpr (SP2) {
;             PG8_LDB(B0, 0, 0); PG8_LDB(B1, 0, 1); PG8_SCHED; PG8_LDA(At, 0, 0); PG8_STAGE(PG8_SA(1, 1), a1 + hstepA, voffA);
;             PG8_WAIT_V(8); PG8_WAIT_L(0); PG8_BAR; PG8_MMA(0, 0, At, B0); PG8_MMA(0, 1, At, B1); PG8_BAR; PG8_SCHED;
;             PG8_LDA(At, 0, 1); PG8_STAGE(PG8_SB(0, 0), b2, voffB); PG8_STAGE(PG8_SB(0, 1), b2 + hstepB, voffB); PG8_STAGE(PG8_SA(0, 0), a2, voffA);
;             PG8_WAIT_V(8); PG8_WAIT_L(0); PG8_BAR; PG8_MMA(1, 0, At, B0); PG8_MMA(1, 1, At, B1); PG8_BAR; PG8_SCHED;
;             PG8_LDB(B0, 1, 0); PG8_LDB(B1, 1, 1); PG8_SCHED; PG8_LDA(At, 1, 0); PG8_STAGE(PG8_SA(0, 1), a2 + hstepA, voffA);
;             PG8_WAIT_V(8); PG8_WAIT_L(0); PG8_BAR; PG8_MMA(0, 0, At, B0); PG8_MMA(0, 1, At, B1); PG8_BAR; PG8_SCHED;
;             PG8_LDA(At, 1, 1); PG8_STAGE(PG8_SB(1, 0), b3, voffB); PG8_STAGE(PG8_SB(1, 1), b3 + hstepB, voffB); PG8_STAGE(PG8_SA(1, 0), a3, voffA);
;             PG8_WAIT_V(8); PG8_WAIT_L(0); PG8_BAR; PG8_MMA(1, 0, At, B0); PG8_MMA(1, 1, At, B1); PG8_BAR; PG8_SCHED;
	s_setprio 1
	s_waitcnt lgkmcnt(0)
	v_mfma_f32_16x16x32_bf16 v[120:123], v[144:147], v[182:185], v[120:123]
	v_mfma_f32_16x16x32_bf16 v[124:127], v[158:161], v[182:185], v[124:127]
	v_mfma_f32_16x16x32_bf16 v[104:107], v[144:147], v[190:193], v[104:107]
	v_mfma_f32_16x16x32_bf16 v[108:111], v[158:161], v[190:193], v[108:111]
	v_mfma_f32_16x16x32_bf16 v[88:91], v[144:147], v[198:201], v[88:91]
	v_mfma_f32_16x16x32_bf16 v[92:95], v[158:161], v[198:201], v[92:95]
	v_mfma_f32_16x16x32_bf16 v[72:75], v[144:147], v[206:209], v[72:75]
	v_mfma_f32_16x16x32_bf16 v[76:79], v[158:161], v[206:209], v[76:79]
	v_mfma_f32_16x16x32_bf16 v[120:123], v[154:157], v[186:189], v[120:123]
	v_mfma_f32_16x16x32_bf16 v[124:127], v[162:165], v[186:189], v[124:127]
	v_mfma_f32_16x16x32_bf16 v[104:107], v[154:157], v[194:197], v[104:107]
	v_mfma_f32_16x16x32_bf16 v[108:111], v[162:165], v[194:197], v[108:111]
	v_mfma_f32_16x16x32_bf16 v[88:91], v[154:157], v[202:205], v[88:91]
	v_mfma_f32_16x16x32_bf16 v[92:95], v[162:165], v[202:205], v[92:95]
	v_mfma_f32_16x16x32_bf16 v[72:75], v[154:157], v[210:213], v[72:75]
	v_mfma_f32_16x16x32_bf16 v[76:79], v[162:165], v[210:213], v[76:79]
	s_setprio 0
	s_setprio 1
	v_mfma_f32_16x16x32_bf16 v[112:115], v[166:169], v[182:185], v[112:115]
	v_mfma_f32_16x16x32_bf16 v[116:119], v[174:177], v[182:185], v[116:119]
	v_mfma_f32_16x16x32_bf16 v[96:99], v[166:169], v[190:193], v[96:99]
	v_mfma_f32_16x16x32_bf16 v[100:103], v[174:177], v[190:193], v[100:103]
	v_mfma_f32_16x16x32_bf16 v[80:83], v[166:169], v[198:201], v[80:83]
	v_mfma_f32_16x16x32_bf16 v[84:87], v[174:177], v[198:201], v[84:87]
	v_mfma_f32_16x16x32_bf16 v[64:67], v[166:169], v[206:209], v[64:67]
	v_mfma_f32_16x16x32_bf16 v[68:71], v[174:177], v[206:209], v[68:71]
	v_mfma_f32_16x16x32_bf16 v[112:115], v[170:173], v[186:189], v[112:115]
	v_mfma_f32_16x16x32_bf16 v[116:119], v[178:181], v[186:189], v[116:119]
	v_mfma_f32_16x16x32_bf16 v[96:99], v[170:173], v[194:197], v[96:99]
	v_mfma_f32_16x16x32_bf16 v[100:103], v[178:181], v[194:197], v[100:103]
	v_mfma_f32_16x16x32_bf16 v[80:83], v[170:173], v[202:205], v[80:83]
	v_mfma_f32_16x16x32_bf16 v[84:87], v[178:181], v[202:205], v[84:87]
	v_mfma_f32_16x16x32_bf16 v[64:67], v[170:173], v[210:213], v[64:67]
	v_mfma_f32_16x16x32_bf16 v[68:71], v[178:181], v[210:213], v[68:71]
	s_setprio 0
	s_barrier
	s_add_i32 s40, s66, s33
	v_lshl_add_u64 v[214:215], v[214:215], 0, s[12:13]
	s_mov_b32 m0, s40
	ds_read_b128 v[182:185], v153 offset:49152
	ds_read_b128 v[186:189], v153 offset:50176
	ds_read_b128 v[190:193], v153 offset:51200
	ds_read_b128 v[194:197], v153 offset:52224
	ds_read_b128 v[198:201], v153 offset:53248
	ds_read_b128 v[202:205], v153 offset:54272
	ds_read_b128 v[206:209], v153 offset:55296
	ds_read_b128 v[210:213], v153 offset:56320
	global_load_lds_dwordx4 v[214:215], off
	s_add_i32 m0, s40, 0x2000
	s_add_u32 s40, s42, 0x160080
	v_lshl_add_u64 v[214:215], v[216:217], 0, s[12:13]
	s_addc_u32 s41, s43, 0
	s_add_i32 s42, s67, s33
	global_load_lds_dwordx4 v[214:215], off
	v_lshl_add_u64 v[214:215], s[40:41], 0, v[130:131]
	s_mov_b32 m0, s42
	s_nop 0
	global_load_lds_dwordx4 v[214:215], off
	v_lshl_add_u64 v[214:215], s[40:41], 0, v[134:135]
	s_add_i32 m0, s42, 0x2000
	s_nop 0
	global_load_lds_dwordx4 v[214:215], off
	s_waitcnt vmcnt(6)
	s_waitcnt lgkmcnt(0)
	s_barrier
	s_setprio 1
	s_waitcnt lgkmcnt(0)
	v_mfma_f32_16x16x32_bf16 v[56:59], v[144:147], v[182:185], v[56:59]
	v_mfma_f32_16x16x32_bf16 v[60:63], v[158:161], v[182:185], v[60:63]
	v_mfma_f32_16x16x32_bf16 v[40:43], v[144:147], v[190:193], v[40:43]
	v_mfma_f32_16x16x32_bf16 v[44:47], v[158:161], v[190:193], v[44:47]
	v_mfma_f32_16x16x32_bf16 v[24:27], v[144:147], v[198:201], v[24:27]
	v_mfma_f32_16x16x32_bf16 v[28:31], v[158:161], v[198:201], v[28:31]
	v_mfma_f32_16x16x32_bf16 v[8:11], v[144:147], v[206:209], v[8:11]
	v_mfma_f32_16x16x32_bf16 v[12:15], v[158:161], v[206:209], v[12:15]
	v_mfma_f32_16x16x32_bf16 v[56:59], v[154:157], v[186:189], v[56:59]
	v_mfma_f32_16x16x32_bf16 v[60:63], v[162:165], v[186:189], v[60:63]
	v_mfma_f32_16x16x32_bf16 v[40:43], v[154:157], v[194:197], v[40:43]
	v_mfma_f32_16x16x32_bf16 v[44:47], v[162:165], v[194:197], v[44:47]
	v_mfma_f32_16x16x32_bf16 v[24:27], v[154:157], v[202:205], v[24:27]
	v_mfma_f32_16x16x32_bf16 v[28:31], v[162:165], v[202:205], v[28:31]
	v_mfma_f32_16x16x32_bf16 v[8:11], v[154:157], v[210:213], v[8:11]
	v_mfma_f32_16x16x32_bf16 v[12:15], v[162:165], v[210:213], v[12:15]
	s_setprio 0
	s_setprio 1
	v_mfma_f32_16x16x32_bf16 v[48:51], v[166:169], v[182:185], v[48:51]
	v_mfma_f32_16x16x32_bf16 v[52:55], v[174:177], v[182:185], v[52:55]
	v_mfma_f32_16x16x32_bf16 v[32:35], v[166:169], v[190:193], v[32:35]
	v_mfma_f32_16x16x32_bf16 v[36:39], v[174:177], v[190:193], v[36:39]
	v_mfma_f32_16x16x32_bf16 v[16:19], v[166:169], v[198:201], v[16:19]
	v_mfma_f32_16x16x32_bf16 v[20:23], v[174:177], v[198:201], v[20:23]
	v_mfma_f32_16x16x32_bf16 v[4:7], v[166:169], v[206:209], v[4:7]
	v_mfma_f32_16x16x32_bf16 v[0:3], v[174:177], v[206:209], v[0:3]
	v_mfma_f32_16x16x32_bf16 v[48:51], v[170:173], v[186:189], v[48:51]
	v_mfma_f32_16x16x32_bf16 v[52:55], v[178:181], v[186:189], v[52:55]
	v_mfma_f32_16x16x32_bf16 v[32:35], v[170:173], v[194:197], v[32:35]
	v_mfma_f32_16x16x32_bf16 v[36:39], v[178:181], v[194:197], v[36:39]
	v_mfma_f32_16x16x32_bf16 v[16:19], v[170:173], v[202:205], v[16:19]
	v_mfma_f32_16x16x32_bf16 v[20:23], v[178:181], v[202:205], v[20:23]
	v_mfma_f32_16x16x32_bf16 v[4:7], v[170:173], v[210:213], v[4:7]
	v_mfma_f32_16x16x32_bf16 v[0:3], v[178:181], v[210:213], v[0:3]
	s_setprio 0
	s_barrier
	s_add_i32 s65, s65, 2
	s_add_u32 s39, s39, 0x100
	s_addc_u32 s64, s64, 0
	s_cmpk_gt_u32 s65, 0x55
	s_mov_b64 s[40:41], s[4:5]
	s_cbranch_scc0 .LBB0_1912
	s_and_b64 vcc, exec, s[14:15]
	s_cbranch_vccz .LBB0_1915
	s_barrier
